# also replace the m3->gates grid barrier by arrive counter + deferred wait before the first gates epilogue (sc1 Y stores in m3)
# speedup vs baseline: 1.0293x; 1.0075x over previous
.LBB0_1220:
	s_or_b64 exec, exec, s[6:7]
	s_waitcnt lgkmcnt(0)
	s_barrier
	s_load_dwordx2 s[4:5], s[0:1], 0x98
	s_lshl_b64 s[6:7], s[72:73], 2
	v_lshlrev_b32_e32 v22, 4, v186
	v_ashrrev_i32_e32 v23, 31, v22
	v_lshlrev_b32_e32 v0, 4, v187
	s_waitcnt lgkmcnt(0)
	s_add_u32 s4, s4, s6
	s_addc_u32 s5, s5, s7
	s_lshl_b32 s6, s89, 2
	s_add_u32 s4, s4, s6
	s_addc_u32 s5, s5, 0
	v_lshl_add_u64 v[2:3], v[22:23], 2, s[4:5]
	v_lshl_add_u64 v[2:3], v[2:3], 0, v[0:1]
	global_load_dwordx4 v[2:5], v[2:3], off
	s_add_u32 s4, s80, s40
	s_addc_u32 s5, s81, 0
	v_lshl_add_u64 v[22:23], v[22:23], 1, s[4:5]
	v_lshlrev_b32_e32 v0, 3, v187
	v_lshl_add_u64 v[22:23], v[22:23], 0, v[0:1]
	v_add_u32_e32 v0, s42, v82
	ds_read_b128 v[24:27], v0
	ds_read_b128 v[28:31], v0 offset:16
	v_or_b32_e32 v52, 16, v193
	v_lshl_add_u32 v0, v52, 5, s42
	s_mov_b32 s4, 0x358637bd
	s_waitcnt lgkmcnt(1)
	v_mov_b32_e32 v32, v25
	v_mov_b32_e32 v33, v26
	v_mov_b32_e32 v25, v27
	v_pk_add_f32 v[32:33], v[32:33], v[24:25]
	s_waitcnt lgkmcnt(0)
	v_mov_b32_e32 v24, v30
	v_mov_b32_e32 v25, v28
	v_mov_b32_e32 v28, v31
	v_pk_add_f32 v[46:47], v[24:25], v[28:29]
	v_or_b32_e32 v24, s63, v193
	v_ashrrev_i32_e32 v25, 31, v24
	v_lshlrev_b64 v[24:25], 10, v[24:25]
	v_lshl_add_u64 v[48:49], v[22:23], 0, v[24:25]
	ds_read_b128 v[24:27], v0
	ds_read_b128 v[28:31], v0 offset:16
	s_brev_b32 s6, 60
	s_waitcnt lgkmcnt(1)
	v_mov_b32_e32 v50, v25
	v_mov_b32_e32 v51, v26
	v_mov_b32_e32 v25, v27
	v_pk_add_f32 v[24:25], v[50:51], v[24:25]
	s_waitcnt lgkmcnt(0)
	v_mov_b32_e32 v26, v30
	v_mov_b32_e32 v27, v28
	v_mov_b32_e32 v28, v31
	v_pk_add_f32 v[26:27], v[26:27], v[28:29]
	v_mov_b32_e32 v28, v24
	v_mov_b32_e32 v29, v32
	v_mov_b32_e32 v32, v25
	v_pk_add_f32 v[24:25], v[28:29], v[32:33]
	v_mov_b32_e32 v28, v27
	v_mov_b32_e32 v29, v47
	v_pk_add_f32 v[24:25], v[24:25], v[28:29]
	v_mov_b32_e32 v27, v46
	v_pk_add_f32 v[26:27], v[26:27], v[24:25]
	v_mov_b64_e32 v[24:25], s[4:5]
	v_pk_fma_f32 v[26:27], v[26:27], s[6:7], v[24:25] op_sel_hi:[1,0,0]
	v_or_b32_e32 v50, 48, v193
	v_mul_f32_e32 v0, 0x4b800000, v27
	v_cmp_gt_f32_e64 s[4:5], s33, v27
	v_cmp_gt_f32_e32 vcc, s33, v26
	s_nop 0
	v_cndmask_b32_e64 v0, v27, v0, s[4:5]
	v_rsq_f32_e32 v0, v0
	s_nop 0
	v_mul_f32_e32 v27, 0x45800000, v0
	v_cndmask_b32_e64 v0, v0, v27, s[4:5]
	v_pk_mul_f32 v[28:29], v[160:161], v[0:1] op_sel_hi:[1,0]
	v_pk_mul_f32 v[30:31], v[158:159], v[0:1] op_sel_hi:[1,0]
	v_mul_f32_e32 v0, 0x4b800000, v26
	v_cndmask_b32_e32 v0, v26, v0, vcc
	v_rsq_f32_e32 v0, v0
	s_waitcnt vmcnt(0)
	v_pk_mul_f32 v[28:29], v[2:3], v[28:29]
	v_pk_mul_f32 v[30:31], v[4:5], v[30:31]
	v_mul_f32_e32 v26, 0x45800000, v0
	v_cvt_pk_bf16_f32 v28, v28, v29
	v_cvt_pk_bf16_f32 v29, v30, v31
	v_cndmask_b32_e32 v0, v0, v26, vcc
	global_store_dwordx2 v[48:49], v[28:29], off sc1
	v_pk_mul_f32 v[26:27], v[42:43], v[0:1] op_sel_hi:[1,0]
	v_pk_mul_f32 v[28:29], v[44:45], v[0:1] op_sel_hi:[1,0]
	v_pk_mul_f32 v[26:27], v[2:3], v[26:27]
	v_pk_mul_f32 v[28:29], v[4:5], v[28:29]
	v_cvt_pk_bf16_f32 v26, v26, v27
	v_cvt_pk_bf16_f32 v27, v28, v29
	v_or_b32_e32 v28, s63, v52
	v_ashrrev_i32_e32 v29, 31, v28
	v_lshlrev_b64 v[28:29], 10, v[28:29]
	v_lshl_add_u64 v[28:29], v[22:23], 0, v[28:29]
	v_or_b32_e32 v0, 32, v193
	global_store_dwordx2 v[28:29], v[26:27], off sc1
	v_lshl_add_u32 v30, v0, 5, s42
	ds_read_b128 v[26:29], v30
	ds_read_b128 v[30:33], v30 offset:16
	s_waitcnt lgkmcnt(1)
	v_mov_b32_e32 v42, v27
	v_mov_b32_e32 v43, v28
	v_mov_b32_e32 v27, v29
	v_pk_add_f32 v[42:43], v[42:43], v[26:27]
	s_waitcnt lgkmcnt(0)
	v_mov_b32_e32 v26, v32
	v_mov_b32_e32 v27, v30
	v_mov_b32_e32 v30, v33
	v_pk_add_f32 v[44:45], v[26:27], v[30:31]
	v_or_b32_e32 v26, s63, v0
	v_ashrrev_i32_e32 v27, 31, v26
	v_lshlrev_b64 v[26:27], 10, v[26:27]
	v_lshl_add_u32 v0, v50, 5, s42
	v_lshl_add_u64 v[46:47], v[22:23], 0, v[26:27]
	ds_read_b128 v[26:29], v0
	ds_read_b128 v[30:33], v0 offset:16
	s_waitcnt lgkmcnt(1)
	v_mov_b32_e32 v48, v27
	v_mov_b32_e32 v49, v28
	v_mov_b32_e32 v27, v29
	v_pk_add_f32 v[26:27], v[48:49], v[26:27]
	s_waitcnt lgkmcnt(0)
	v_mov_b32_e32 v28, v32
	v_mov_b32_e32 v29, v30
	v_mov_b32_e32 v30, v33
	v_pk_add_f32 v[28:29], v[28:29], v[30:31]
	v_mov_b32_e32 v30, v26
	v_mov_b32_e32 v31, v42
	v_mov_b32_e32 v42, v27
	v_pk_add_f32 v[26:27], v[30:31], v[42:43]
	v_mov_b32_e32 v30, v29
	v_mov_b32_e32 v31, v45
	v_pk_add_f32 v[26:27], v[26:27], v[30:31]
	v_mov_b32_e32 v29, v44
	v_pk_add_f32 v[26:27], v[28:29], v[26:27]
	v_or_b32_e32 v42, 0x50, v193
	v_pk_fma_f32 v[26:27], v[26:27], s[6:7], v[24:25] op_sel_hi:[1,0,0]
	s_nop 0
	v_mul_f32_e32 v0, 0x4b800000, v27
	v_cmp_gt_f32_e64 s[4:5], s33, v27
	v_cmp_gt_f32_e32 vcc, s33, v26
	s_nop 0
	v_cndmask_b32_e64 v0, v27, v0, s[4:5]
	v_rsq_f32_e32 v0, v0
	s_nop 0
	v_mul_f32_e32 v27, 0x45800000, v0
	v_cndmask_b32_e64 v0, v0, v27, s[4:5]
	v_pk_mul_f32 v[28:29], v[38:39], v[0:1] op_sel_hi:[1,0]
	v_pk_mul_f32 v[30:31], v[40:41], v[0:1] op_sel_hi:[1,0]
	v_mul_f32_e32 v0, 0x4b800000, v26
	v_cndmask_b32_e32 v0, v26, v0, vcc
	v_rsq_f32_e32 v0, v0
	v_pk_mul_f32 v[28:29], v[2:3], v[28:29]
	v_pk_mul_f32 v[30:31], v[4:5], v[30:31]
	v_cvt_pk_bf16_f32 v28, v28, v29
	v_mul_f32_e32 v26, 0x45800000, v0
	v_cvt_pk_bf16_f32 v29, v30, v31
	v_cndmask_b32_e32 v0, v0, v26, vcc
	global_store_dwordx2 v[46:47], v[28:29], off sc1
	v_pk_mul_f32 v[26:27], v[34:35], v[0:1] op_sel_hi:[1,0]
	v_pk_mul_f32 v[28:29], v[36:37], v[0:1] op_sel_hi:[1,0]
	v_pk_mul_f32 v[26:27], v[2:3], v[26:27]
	v_pk_mul_f32 v[28:29], v[4:5], v[28:29]
	v_cvt_pk_bf16_f32 v26, v26, v27
	v_cvt_pk_bf16_f32 v27, v28, v29
	v_or_b32_e32 v28, s63, v50
	v_ashrrev_i32_e32 v29, 31, v28
	v_lshlrev_b64 v[28:29], 10, v[28:29]
	v_lshl_add_u64 v[28:29], v[22:23], 0, v[28:29]
	v_or_b32_e32 v0, 64, v193
	global_store_dwordx2 v[28:29], v[26:27], off sc1
	v_lshl_add_u32 v30, v0, 5, s42
	ds_read_b128 v[26:29], v30
	ds_read_b128 v[30:33], v30 offset:16
	s_waitcnt lgkmcnt(1)
	v_mov_b32_e32 v34, v27
	v_mov_b32_e32 v35, v28
	v_mov_b32_e32 v27, v29
	v_pk_add_f32 v[34:35], v[34:35], v[26:27]
	s_waitcnt lgkmcnt(0)
	v_mov_b32_e32 v26, v32
	v_mov_b32_e32 v27, v30
	v_mov_b32_e32 v30, v33
	v_pk_add_f32 v[36:37], v[26:27], v[30:31]
	v_or_b32_e32 v26, s63, v0
	v_ashrrev_i32_e32 v27, 31, v26
	v_lshlrev_b64 v[26:27], 10, v[26:27]
	v_lshl_add_u32 v0, v42, 5, s42
	v_lshl_add_u64 v[38:39], v[22:23], 0, v[26:27]
	ds_read_b128 v[26:29], v0
	ds_read_b128 v[30:33], v0 offset:16
	s_waitcnt lgkmcnt(1)
	v_mov_b32_e32 v40, v27
	v_mov_b32_e32 v41, v28
	v_mov_b32_e32 v27, v29
	v_pk_add_f32 v[26:27], v[40:41], v[26:27]
	s_waitcnt lgkmcnt(0)
	v_mov_b32_e32 v28, v32
	v_mov_b32_e32 v29, v30
	v_mov_b32_e32 v30, v33
	v_pk_add_f32 v[28:29], v[28:29], v[30:31]
	v_mov_b32_e32 v30, v26
	v_mov_b32_e32 v31, v34
	v_mov_b32_e32 v34, v27
	v_pk_add_f32 v[26:27], v[30:31], v[34:35]
	v_mov_b32_e32 v30, v29
	v_mov_b32_e32 v31, v37
	v_pk_add_f32 v[26:27], v[26:27], v[30:31]
	v_mov_b32_e32 v29, v36
	v_pk_add_f32 v[26:27], v[28:29], v[26:27]
	v_or_b32_e32 v34, 0x70, v193
	v_pk_fma_f32 v[26:27], v[26:27], s[6:7], v[24:25] op_sel_hi:[1,0,0]
	s_nop 0
	v_mul_f32_e32 v0, 0x4b800000, v27
	v_cmp_gt_f32_e64 s[4:5], s33, v27
	v_cmp_gt_f32_e32 vcc, s33, v26
	s_nop 0
	v_cndmask_b32_e64 v0, v27, v0, s[4:5]
	v_rsq_f32_e32 v0, v0
	s_nop 0
	v_mul_f32_e32 v27, 0x45800000, v0
	v_cndmask_b32_e64 v0, v0, v27, s[4:5]
	v_pk_mul_f32 v[14:15], v[14:15], v[0:1] op_sel_hi:[1,0]
	v_pk_mul_f32 v[16:17], v[16:17], v[0:1] op_sel_hi:[1,0]
	v_mul_f32_e32 v0, 0x4b800000, v26
	v_cndmask_b32_e32 v0, v26, v0, vcc
	v_rsq_f32_e32 v0, v0
	v_pk_mul_f32 v[14:15], v[2:3], v[14:15]
	v_pk_mul_f32 v[16:17], v[4:5], v[16:17]
	v_cvt_pk_bf16_f32 v14, v14, v15
	v_cvt_pk_bf16_f32 v15, v16, v17
	global_store_dwordx2 v[38:39], v[14:15], off sc1
	v_mul_f32_e32 v14, 0x45800000, v0
	v_cndmask_b32_e32 v0, v0, v14, vcc
	v_pk_mul_f32 v[14:15], v[18:19], v[0:1] op_sel_hi:[1,0]
	v_pk_mul_f32 v[16:17], v[20:21], v[0:1] op_sel_hi:[1,0]
	v_pk_mul_f32 v[14:15], v[2:3], v[14:15]
	v_pk_mul_f32 v[16:17], v[4:5], v[16:17]
	v_cvt_pk_bf16_f32 v14, v14, v15
	v_cvt_pk_bf16_f32 v15, v16, v17
	v_or_b32_e32 v16, s63, v42
	v_ashrrev_i32_e32 v17, 31, v16
	v_lshlrev_b64 v[16:17], 10, v[16:17]
	v_lshl_add_u64 v[16:17], v[22:23], 0, v[16:17]
	v_or_b32_e32 v0, 0x60, v193
	global_store_dwordx2 v[16:17], v[14:15], off sc1
	v_lshl_add_u32 v18, v0, 5, s42
	ds_read_b128 v[14:17], v18
	ds_read_b128 v[18:21], v18 offset:16
	s_waitcnt lgkmcnt(1)
	v_mov_b32_e32 v26, v15
	v_mov_b32_e32 v27, v16
	v_mov_b32_e32 v15, v17
	v_pk_add_f32 v[26:27], v[26:27], v[14:15]
	s_waitcnt lgkmcnt(0)
	v_mov_b32_e32 v14, v20
	v_mov_b32_e32 v15, v18
	v_mov_b32_e32 v18, v21
	v_pk_add_f32 v[28:29], v[14:15], v[18:19]
	v_or_b32_e32 v14, s63, v0
	v_ashrrev_i32_e32 v15, 31, v14
	v_lshlrev_b64 v[14:15], 10, v[14:15]
	v_lshl_add_u32 v0, v34, 5, s42
	v_lshl_add_u64 v[30:31], v[22:23], 0, v[14:15]
	ds_read_b128 v[14:17], v0
	ds_read_b128 v[18:21], v0 offset:16
	s_waitcnt lgkmcnt(1)
	v_mov_b32_e32 v32, v15
	v_mov_b32_e32 v33, v16
	v_mov_b32_e32 v15, v17
	v_pk_add_f32 v[14:15], v[32:33], v[14:15]
	s_waitcnt lgkmcnt(0)
	v_mov_b32_e32 v16, v20
	v_mov_b32_e32 v17, v18
	v_mov_b32_e32 v18, v21
	v_pk_add_f32 v[16:17], v[16:17], v[18:19]
	v_mov_b32_e32 v18, v14
	v_mov_b32_e32 v19, v26
	v_mov_b32_e32 v26, v15
	v_pk_add_f32 v[14:15], v[18:19], v[26:27]
	v_mov_b32_e32 v18, v17
	v_mov_b32_e32 v19, v29
	v_pk_add_f32 v[14:15], v[14:15], v[18:19]
	v_mov_b32_e32 v17, v28
	v_pk_add_f32 v[14:15], v[16:17], v[14:15]
	s_nop 0
	v_pk_fma_f32 v[14:15], v[14:15], s[6:7], v[24:25] op_sel_hi:[1,0,0]
	s_nop 0
	v_mul_f32_e32 v0, 0x4b800000, v15
	v_cmp_gt_f32_e64 s[4:5], s33, v15
	v_cmp_gt_f32_e32 vcc, s33, v14
	s_nop 0
	v_cndmask_b32_e64 v0, v15, v0, s[4:5]
	v_rsq_f32_e32 v0, v0
	s_nop 0
	v_mul_f32_e32 v15, 0x45800000, v0
	v_cndmask_b32_e64 v0, v0, v15, s[4:5]
	v_pk_mul_f32 v[6:7], v[6:7], v[0:1] op_sel_hi:[1,0]
	v_pk_mul_f32 v[8:9], v[8:9], v[0:1] op_sel_hi:[1,0]
	v_mul_f32_e32 v0, 0x4b800000, v14
	v_cndmask_b32_e32 v0, v14, v0, vcc
	v_rsq_f32_e32 v0, v0
	v_pk_mul_f32 v[6:7], v[2:3], v[6:7]
	v_pk_mul_f32 v[8:9], v[4:5], v[8:9]
	v_cvt_pk_bf16_f32 v6, v6, v7
	v_cvt_pk_bf16_f32 v7, v8, v9
	global_store_dwordx2 v[30:31], v[6:7], off sc1
	v_mul_f32_e32 v6, 0x45800000, v0
	v_cndmask_b32_e32 v0, v0, v6, vcc
	v_pk_mul_f32 v[6:7], v[10:11], v[0:1] op_sel_hi:[1,0]
	s_nop 0
	v_pk_mul_f32 v[2:3], v[2:3], v[6:7]
	v_pk_mul_f32 v[6:7], v[12:13], v[0:1] op_sel_hi:[1,0]
	v_cvt_pk_bf16_f32 v2, v2, v3
	v_pk_mul_f32 v[4:5], v[4:5], v[6:7]
	s_nop 0
	v_cvt_pk_bf16_f32 v3, v4, v5
	v_or_b32_e32 v4, s63, v34
	v_ashrrev_i32_e32 v5, 31, v4
	v_lshlrev_b64 v[4:5], 10, v[4:5]
	v_lshl_add_u64 v[4:5], v[22:23], 0, v[4:5]
	global_store_dwordx2 v[4:5], v[2:3], off sc1
	s_waitcnt lgkmcnt(0)
	s_barrier

.LBB0_1309:
	s_or_b64 exec, exec, s[4:5]
	s_waitcnt lgkmcnt(0)
	ds_read_b128 v[4:7], v2 offset:49280
	ds_read_b128 v[8:11], v2 offset:49312
	s_lshl_b64 s[4:5], s[8:9], 10
	s_add_u32 s4, s84, s4
	s_addc_u32 s5, s85, s5
	s_waitcnt lgkmcnt(1)
	v_rcp_f32_e32 v0, v4
	v_rcp_f32_e32 v3, v5
	v_rcp_f32_e32 v12, v6
	v_rcp_f32_e32 v13, v7
	s_waitcnt lgkmcnt(0)
	v_rcp_f32_e32 v14, v8
	ds_read_b128 v[4:7], v2 offset:49344
	v_rcp_f32_e32 v15, v9
	v_rcp_f32_e32 v48, v10
	v_rcp_f32_e32 v49, v11
	ds_read_b128 v[8:11], v2 offset:49376
	s_lshl_b32 s6, s30, 1
	s_add_u32 s6, s4, s6
	s_addc_u32 s7, s5, 0
	s_lshl_b32 s8, s40, 12
	s_waitcnt lgkmcnt(1)
	v_rcp_f32_e32 v2, v4
	v_rcp_f32_e32 v4, v5
	v_rcp_f32_e32 v5, v6
	v_rcp_f32_e32 v6, v7
	s_waitcnt lgkmcnt(0)
	v_rcp_f32_e32 v7, v8
	v_rcp_f32_e32 v8, v9
	v_rcp_f32_e32 v9, v10
	v_rcp_f32_e32 v10, v11
	s_add_i32 s8, s8, 0
	v_lshlrev_b32_e32 v11, 9, v227
	v_lshlrev_b32_e32 v50, 1, v226
	v_mul_f32_e32 v32, v32, v0
	v_mul_f32_e32 v0, v16, v0
	v_add3_u32 v11, s8, v11, v50
	v_cvt_pk_bf16_f32 v0, v0, s0
	ds_write_b16 v11, v0 offset:51264
	v_mul_f32_e32 v0, v33, v3
	v_cvt_pk_bf16_f32 v0, v0, s0
	ds_write_b16 v11, v0 offset:51328
	v_mul_f32_e32 v0, v17, v3
	v_cvt_pk_bf16_f32 v0, v0, s0
	ds_write_b16 v11, v0 offset:51392
	v_mul_f32_e32 v0, v34, v12
	v_cvt_pk_bf16_f32 v0, v0, s0
	ds_write_b16 v11, v0 offset:51456
	v_mul_f32_e32 v0, v18, v12
	v_cvt_pk_bf16_f32 v0, v0, s0
	ds_write_b16 v11, v0 offset:51520
	v_mul_f32_e32 v0, v35, v13
	v_cvt_pk_bf16_f32 v0, v0, s0
	ds_write_b16 v11, v0 offset:51584
	v_mul_f32_e32 v0, v19, v13
	v_cvt_pk_bf16_f32 v0, v0, s0
	ds_write_b16 v11, v0 offset:51648
	v_mul_f32_e32 v0, v36, v14
	v_cvt_pk_bf16_f32 v0, v0, s0
	ds_write_b16 v11, v0 offset:52224
	v_mul_f32_e32 v0, v20, v14
	v_cvt_pk_bf16_f32 v0, v0, s0
	ds_write_b16 v11, v0 offset:52288
	v_mul_f32_e32 v0, v37, v15
	v_cvt_pk_bf16_f32 v0, v0, s0
	ds_write_b16 v11, v0 offset:52352
	v_mul_f32_e32 v0, v21, v15
	v_cvt_pk_bf16_f32 v0, v0, s0
	ds_write_b16 v11, v0 offset:52416
	v_mul_f32_e32 v0, v38, v48
	v_cvt_pk_bf16_f32 v0, v0, s0
	ds_write_b16 v11, v0 offset:52480
	v_mul_f32_e32 v0, v22, v48
	v_cvt_pk_bf16_f32 v0, v0, s0
	ds_write_b16 v11, v0 offset:52544
	v_mul_f32_e32 v0, v39, v49
	v_cvt_pk_bf16_f32 v0, v0, s0
	ds_write_b16 v11, v0 offset:52608
	v_mul_f32_e32 v0, v23, v49
	v_cvt_pk_bf16_f32 v0, v0, s0
	ds_write_b16 v11, v0 offset:52672
	v_mul_f32_e32 v0, v40, v2
	v_cvt_pk_bf16_f32 v0, v0, s0
	ds_write_b16 v11, v0 offset:53248
	v_mul_f32_e32 v0, v24, v2
	v_cvt_pk_bf16_f32 v0, v0, s0
	ds_write_b16 v11, v0 offset:53312
	v_mul_f32_e32 v0, v41, v4
	v_cvt_pk_bf16_f32 v0, v0, s0
	ds_write_b16 v11, v0 offset:53376
	v_mul_f32_e32 v0, v25, v4
	v_cvt_pk_bf16_f32 v0, v0, s0
	ds_write_b16 v11, v0 offset:53440
	v_mul_f32_e32 v0, v42, v5
	v_cvt_pk_bf16_f32 v0, v0, s0
	ds_write_b16 v11, v0 offset:53504
	v_mul_f32_e32 v0, v26, v5
	v_cvt_pk_bf16_f32 v0, v0, s0
	ds_write_b16 v11, v0 offset:53568
	v_mul_f32_e32 v0, v43, v6
	v_cvt_pk_bf16_f32 v0, v0, s0
	ds_write_b16 v11, v0 offset:53632
	v_mul_f32_e32 v0, v27, v6
	v_cvt_pk_bf16_f32 v0, v0, s0
	ds_write_b16 v11, v0 offset:53696
	v_mul_f32_e32 v0, v44, v7
	v_cvt_pk_bf16_f32 v0, v0, s0
	ds_write_b16 v11, v0 offset:54272
	v_mul_f32_e32 v0, v28, v7
	v_cvt_pk_bf16_f32 v0, v0, s0
	ds_write_b16 v11, v0 offset:54336
	v_mul_f32_e32 v0, v45, v8
	v_cvt_pk_bf16_f32 v0, v0, s0
	ds_write_b16 v11, v0 offset:54400
	v_mul_f32_e32 v0, v29, v8
	v_cvt_pk_bf16_f32 v0, v0, s0
	ds_write_b16 v11, v0 offset:54464
	v_mul_f32_e32 v0, v46, v9
	v_cvt_pk_bf16_f32 v0, v0, s0
	ds_write_b16 v11, v0 offset:54528
	v_mul_f32_e32 v0, v30, v9
	v_cvt_pk_bf16_f32 v0, v0, s0
	ds_write_b16 v11, v0 offset:54592
	v_mul_f32_e32 v0, v47, v10
	v_cvt_pk_bf16_f32 v0, v0, s0
	ds_write_b16 v11, v0 offset:54656
	v_mul_f32_e32 v0, v31, v10
	v_cvt_pk_bf16_f32 v0, v0, s0
	s_lshl_b64 s[4:5], s[10:11], 10
	ds_write_b16 v11, v0 offset:54720
	v_lshlrev_b32_e32 v0, 1, v225
	v_cvt_pk_bf16_f32 v32, v32, s0
	s_add_u32 s4, s6, s4
	v_and_b32_e32 v0, 0x70, v0
	ds_write_b16 v11, v32 offset:51200
	s_addc_u32 s5, s7, s5
	v_lshrrev_b32_e32 v14, 3, v224
	v_add_u32_e32 v15, s8, v0
	s_waitcnt lgkmcnt(0)
	v_lshl_add_u64 v[10:11], s[4:5], 0, v[0:1]
	v_lshl_add_u32 v0, v14, 7, v15
	v_or_b32_e32 v16, 8, v14
	ds_read_b128 v[2:5], v0 offset:51200
	v_lshl_add_u32 v6, v16, 7, v15
	ds_read_b128 v[6:9], v6 offset:51200
	v_lshlrev_b32_e32 v0, 10, v14
	v_lshl_add_u64 v[12:13], v[10:11], 0, v[0:1]
	v_lshlrev_b32_e32 v0, 10, v16
	s_waitcnt lgkmcnt(1)
	global_store_dwordx4 v[12:13], v[2:5], off sc1
	s_mov_b64 s[4:5], 0
	s_nop 0
	v_lshl_add_u64 v[2:3], v[10:11], 0, v[0:1]
	v_or_b32_e32 v0, 16, v14
	s_waitcnt lgkmcnt(0)
	global_store_dwordx4 v[2:3], v[6:9], off sc1
	v_lshl_add_u32 v2, v0, 7, v15
	v_or_b32_e32 v14, 24, v14
	ds_read_b128 v[2:5], v2 offset:51200
	v_lshl_add_u32 v6, v14, 7, v15
	ds_read_b128 v[6:9], v6 offset:51200
	v_lshlrev_b32_e32 v0, 10, v0
	v_lshl_add_u64 v[12:13], v[10:11], 0, v[0:1]
	v_lshlrev_b32_e32 v0, 10, v14
	s_waitcnt lgkmcnt(1)
	global_store_dwordx4 v[12:13], v[2:5], off sc1
	s_nop 1
	v_lshl_add_u64 v[2:3], v[10:11], 0, v[0:1]
	s_waitcnt lgkmcnt(0)
	global_store_dwordx4 v[2:3], v[6:9], off sc1
	s_waitcnt lgkmcnt(0)
	s_barrier

.LBB0_1398:
	s_mov_b64 s[4:5], s[76:77]
	s_mov_b32 s0, s3
	s_mov_b32 s1, -1
	s_getreg_b32 s6, hwreg(HW_REG_XCC_ID, 0, 4)
	s_nop 0
	v_mbcnt_lo_u32_b32 v0, s1, 0
	v_mbcnt_hi_u32_b32 v0, s1, v0
	v_lshl_add_u32 v0, s0, 6, v0
	s_waitcnt vmcnt(0)
	s_nop 0
	v_cmp_eq_u32_e32 vcc, 0, v0
	s_barrier
	s_and_saveexec_b64 s[0:1], vcc
	s_mov_b32 s60, 0x10000
	s_cbranch_execz .LBB0_1450
	s_load_dwordx2 s[4:5], s[4:5], 0xb8
	v_mov_b32_e32 v0, 0
	v_mov_b32_e32 v2, 1
	s_waitcnt vmcnt(0) lgkmcnt(0)
	global_atomic_add v0, v2, s[4:5] offset:3072

.LBB0_1462:
	s_cmp_lg_u32 s83, 1
	s_cbranch_scc1 .Lw4_nowait
	s_cmp_lg_u32 s3, 0
	s_cbranch_scc1 .Lw4_bar
	s_load_dwordx2 s[98:99], s[76:77], 0xb8
	s_lshl_b32 vcc_lo, s96, 1
	v_readlane_b32 vcc_hi, v255, 26
	s_cmp_eq_u32 vcc_hi, -1
	s_cselect_b32 vcc_lo, s96, vcc_lo
	v_mov_b32_e32 v0, 0
	s_mov_b32 m0, 0
	s_waitcnt lgkmcnt(0)
.Lw4_spin:
	global_load_dword v134, v0, s[98:99] offset:3072 sc1
	s_waitcnt vmcnt(0)
	v_readfirstlane_b32 vcc_hi, v134
	s_cmp_ge_u32 vcc_hi, vcc_lo
	s_cbranch_scc1 .Lw4_done
	s_add_u32 m0, m0, 1
	s_cmp_gt_u32 m0, 0x100000
	s_cbranch_scc1 .Lw4_done
	s_sleep 1
	s_branch .Lw4_spin

.Lw4_bar:
	s_barrier
.Lw4_nowait:
	v_mul_f32_e32 v0, 0xbfb8aa3b, v126
	v_mul_f32_e32 v134, 0xbfb8aa3b, v118
	v_mul_f32_e32 v135, 0xbfb8aa3b, v127
	v_mul_f32_e32 v136, 0xbfb8aa3b, v119
	v_mul_f32_e32 v137, 0xbfb8aa3b, v128
	v_mul_f32_e32 v151, 0xbfb8aa3b, v120
	v_mul_f32_e32 v153, 0xbfb8aa3b, v129
	v_mul_f32_e32 v155, 0xbfb8aa3b, v121
	v_mul_f32_e32 v158, 0xbfb8aa3b, v122
	v_mul_f32_e32 v159, 0xbfb8aa3b, v114
	v_mul_f32_e32 v160, 0xbfb8aa3b, v123
	v_mul_f32_e32 v161, 0xbfb8aa3b, v115
	v_mul_f32_e32 v162, 0xbfb8aa3b, v124
	v_mul_f32_e32 v163, 0xbfb8aa3b, v116
	v_mul_f32_e32 v164, 0xbfb8aa3b, v125
	v_mul_f32_e32 v165, 0xbfb8aa3b, v117
	v_mul_f32_e32 v170, 0xbfb8aa3b, v110
	v_mul_f32_e32 v171, 0xbfb8aa3b, v102
	v_mul_f32_e32 v172, 0xbfb8aa3b, v111
	v_mul_f32_e32 v173, 0xbfb8aa3b, v103
	v_mul_f32_e32 v174, 0xbfb8aa3b, v112
	v_mul_f32_e32 v175, 0xbfb8aa3b, v104
	v_mul_f32_e32 v176, 0xbfb8aa3b, v113
	v_mul_f32_e32 v177, 0xbfb8aa3b, v105
	v_mul_f32_e32 v178, 0xbfb8aa3b, v106
	v_mul_f32_e32 v179, 0xbfb8aa3b, v98
	v_mul_f32_e32 v180, 0xbfb8aa3b, v107
	v_mul_f32_e32 v181, 0xbfb8aa3b, v99
	v_mul_f32_e32 v182, 0xbfb8aa3b, v108
	v_mul_f32_e32 v183, 0xbfb8aa3b, v100
	v_mul_f32_e32 v184, 0xbfb8aa3b, v109
	v_mul_f32_e32 v185, 0xbfb8aa3b, v101
	v_mul_f32_e32 v186, 0xbfb8aa3b, v94
	v_mul_f32_e32 v187, 0xbfb8aa3b, v86
	v_mul_f32_e32 v188, 0xbfb8aa3b, v95
	v_mul_f32_e32 v189, 0xbfb8aa3b, v87
	v_mul_f32_e32 v190, 0xbfb8aa3b, v96
	v_mul_f32_e32 v191, 0xbfb8aa3b, v88
	v_mul_f32_e32 v192, 0xbfb8aa3b, v97
	v_mul_f32_e32 v193, 0xbfb8aa3b, v89
	v_mul_f32_e32 v194, 0xbfb8aa3b, v90
	v_mul_f32_e32 v195, 0xbfb8aa3b, v82
	v_mul_f32_e32 v196, 0xbfb8aa3b, v91
	v_mul_f32_e32 v197, 0xbfb8aa3b, v83
	v_mul_f32_e32 v204, 0xbfb8aa3b, v92
	v_mul_f32_e32 v220, 0xbfb8aa3b, v84
	v_mul_f32_e32 v221, 0xbfb8aa3b, v93
	v_mul_f32_e32 v219, 0xbfb8aa3b, v85
	v_exp_f32_e32 v254, v0
	v_exp_f32_e32 v246, v134
	v_exp_f32_e32 v253, v135
	v_exp_f32_e32 v245, v136
	v_exp_f32_e32 v252, v137
	v_exp_f32_e32 v244, v151
	v_exp_f32_e32 v251, v153
	v_exp_f32_e32 v243, v155
	v_exp_f32_e32 v250, v158
	v_exp_f32_e32 v242, v159
	v_exp_f32_e32 v249, v160
	v_exp_f32_e32 v241, v161
	v_exp_f32_e32 v248, v162
	v_exp_f32_e32 v240, v163
	v_exp_f32_e32 v247, v164
	v_exp_f32_e32 v239, v165
	v_exp_f32_e32 v238, v170
	v_exp_f32_e32 v230, v171
	v_exp_f32_e32 v237, v172
	v_exp_f32_e32 v229, v173
	v_exp_f32_e32 v236, v174
	v_exp_f32_e32 v228, v175
	v_exp_f32_e32 v235, v176
	v_exp_f32_e32 v227, v177
	v_exp_f32_e32 v234, v178
	v_exp_f32_e32 v226, v179
	v_exp_f32_e32 v233, v180
	v_exp_f32_e32 v225, v181
	v_exp_f32_e32 v232, v182
	v_exp_f32_e32 v224, v183
	v_exp_f32_e32 v231, v184
	v_exp_f32_e32 v223, v185
	v_exp_f32_e32 v211, v186
	v_exp_f32_e32 v203, v187
	v_exp_f32_e32 v210, v188
	v_exp_f32_e32 v202, v189
	v_exp_f32_e32 v209, v190
	v_exp_f32_e32 v201, v191
	v_exp_f32_e32 v208, v192
	v_exp_f32_e32 v200, v193
	v_exp_f32_e32 v207, v194
	v_exp_f32_e32 v199, v195
	v_exp_f32_e32 v206, v196
	v_exp_f32_e32 v198, v197
	v_exp_f32_e32 v205, v204
	v_exp_f32_e32 v197, v220
	v_exp_f32_e32 v204, v221
	v_exp_f32_e32 v196, v219
	v_lshl_add_u32 v156, s26, 8, v166
	v_or_b32_e32 v154, 16, v156
	v_or_b32_e32 v152, 32, v156
	v_or_b32_e32 v150, 48, v156
	s_mov_b64 s[26:27], -1
	s_cmp_gt_i32 s20, 5
	v_ashrrev_i32_e32 v157, 31, v156
	v_ashrrev_i32_e32 v155, 31, v154
	v_ashrrev_i32_e32 v153, 31, v152
	v_ashrrev_i32_e32 v151, 31, v150
	v_mul_f32_e32 v195, 0xbfb8aa3b, v78
	v_mul_f32_e32 v187, 0xbfb8aa3b, v70
	v_mul_f32_e32 v194, 0xbfb8aa3b, v79
	v_mul_f32_e32 v186, 0xbfb8aa3b, v71
	v_mul_f32_e32 v193, 0xbfb8aa3b, v80
	v_mul_f32_e32 v185, 0xbfb8aa3b, v72
	v_mul_f32_e32 v192, 0xbfb8aa3b, v81
	v_mul_f32_e32 v184, 0xbfb8aa3b, v73
	v_mul_f32_e32 v191, 0xbfb8aa3b, v74
	v_mul_f32_e32 v183, 0xbfb8aa3b, v66
	v_mul_f32_e32 v190, 0xbfb8aa3b, v75
	v_mul_f32_e32 v182, 0xbfb8aa3b, v67
	v_mul_f32_e32 v189, 0xbfb8aa3b, v76
	v_mul_f32_e32 v181, 0xbfb8aa3b, v68
	v_mul_f32_e32 v188, 0xbfb8aa3b, v77
	v_mul_f32_e32 v180, 0xbfb8aa3b, v69
	v_mul_f32_e32 v179, 0xbfb8aa3b, v62
	v_mul_f32_e32 v174, 0xbfb8aa3b, v54
	v_mul_f32_e32 v178, 0xbfb8aa3b, v63
	v_mul_f32_e32 v173, 0xbfb8aa3b, v55
	v_mul_f32_e32 v177, 0xbfb8aa3b, v64
	v_mul_f32_e32 v172, 0xbfb8aa3b, v56
	v_mul_f32_e32 v176, 0xbfb8aa3b, v65
	v_mul_f32_e32 v171, 0xbfb8aa3b, v57
	v_mul_f32_e32 v175, 0xbfb8aa3b, v58
	v_mul_f32_e32 v170, 0xbfb8aa3b, v50
	s_cbranch_scc1 .LBB0_1465
	s_andn2_b64 vcc, exec, s[26:27]
	s_cbranch_vccz .LBB0_1466
